# GEMM K-loops: odd half-step W register loads issued interleaved between the MFMA groups instead of ahead of them
# baseline (speedup 1.0000x reference)
.Lg1_nda1:
.Lg1_sada1:
	ds_read_b128 v[198:201], v245 offset:0
	ds_read_b128 v[202:205], v245 offset:2048
	ds_read_b128 v[210:213], v245 offset:4096
	ds_read_b128 v[214:217], v245 offset:6144
	s_waitcnt lgkmcnt(4)
	v_mfma_f32_16x16x32_bf16 v[16:19], v[128:131], v[218:221], v[16:19]
	v_mfma_f32_16x16x32_bf16 v[48:51], v[132:135], v[218:221], v[48:51]
	v_mfma_f32_16x16x32_bf16 v[80:83], v[136:139], v[218:221], v[80:83]
	v_mfma_f32_16x16x32_bf16 v[112:115], v[140:143], v[218:221], v[112:115]
	v_mfma_f32_16x16x32_bf16 v[20:23], v[128:131], v[222:225], v[20:23]
	v_mfma_f32_16x16x32_bf16 v[52:55], v[132:135], v[222:225], v[52:55]
	v_mfma_f32_16x16x32_bf16 v[84:87], v[136:139], v[222:225], v[84:87]
	v_mfma_f32_16x16x32_bf16 v[116:119], v[140:143], v[222:225], v[116:119]
	v_mfma_f32_16x16x32_bf16 v[24:27], v[128:131], v[226:229], v[24:27]
	v_mfma_f32_16x16x32_bf16 v[56:59], v[132:135], v[226:229], v[56:59]
	v_mfma_f32_16x16x32_bf16 v[88:91], v[136:139], v[226:229], v[88:91]
	v_mfma_f32_16x16x32_bf16 v[120:123], v[140:143], v[226:229], v[120:123]
	v_mfma_f32_16x16x32_bf16 v[28:31], v[128:131], v[230:233], v[28:31]
	v_mfma_f32_16x16x32_bf16 v[60:63], v[132:135], v[230:233], v[60:63]
	v_mfma_f32_16x16x32_bf16 v[92:95], v[136:139], v[230:233], v[92:95]
	v_mfma_f32_16x16x32_bf16 v[124:127], v[140:143], v[230:233], v[124:127]
	ds_read_b128 v[218:221], v245 offset:8192
	ds_read_b128 v[222:225], v245 offset:10240
	ds_read_b128 v[226:229], v245 offset:12288
	ds_read_b128 v[230:233], v245 offset:14336
	s_waitcnt vmcnt(16)
	s_waitcnt lgkmcnt(4)
	v_mfma_f32_16x16x32_bf16 v[0:3], v[144:147], v[198:201], v[0:3]
	v_mfma_f32_16x16x32_bf16 v[32:35], v[148:151], v[198:201], v[32:35]
	v_mfma_f32_16x16x32_bf16 v[64:67], v[152:155], v[198:201], v[64:67]
	v_mfma_f32_16x16x32_bf16 v[96:99], v[156:159], v[198:201], v[96:99]
	global_load_dwordx4 v[128:131], v238, s[56:57]
	v_mfma_f32_16x16x32_bf16 v[4:7], v[144:147], v[202:205], v[4:7]
	v_mfma_f32_16x16x32_bf16 v[36:39], v[148:151], v[202:205], v[36:39]
	v_mfma_f32_16x16x32_bf16 v[68:71], v[152:155], v[202:205], v[68:71]
	v_mfma_f32_16x16x32_bf16 v[100:103], v[156:159], v[202:205], v[100:103]
	global_load_dwordx4 v[132:135], v239, s[56:57]
	v_mfma_f32_16x16x32_bf16 v[8:11], v[144:147], v[210:213], v[8:11]
	v_mfma_f32_16x16x32_bf16 v[40:43], v[148:151], v[210:213], v[40:43]
	v_mfma_f32_16x16x32_bf16 v[72:75], v[152:155], v[210:213], v[72:75]
	v_mfma_f32_16x16x32_bf16 v[104:107], v[156:159], v[210:213], v[104:107]
	global_load_dwordx4 v[136:139], v240, s[56:57]
	v_mfma_f32_16x16x32_bf16 v[12:15], v[144:147], v[214:217], v[12:15]
	v_mfma_f32_16x16x32_bf16 v[44:47], v[148:151], v[214:217], v[44:47]
	v_mfma_f32_16x16x32_bf16 v[76:79], v[152:155], v[214:217], v[76:79]
	v_mfma_f32_16x16x32_bf16 v[108:111], v[156:159], v[214:217], v[108:111]
	global_load_dwordx4 v[140:143], v241, s[56:57]
	s_cmp_eq_u32 s25, 31
	s_cbranch_scc1 .Lg1_sww2
	s_add_u32 s56, s56, 1024
	s_addc_u32 s57, s57, 0
	s_branch .Lg1_swdw2

.Lg1_ndw2:
.Lg1_swdw2:
	s_add_i32 s25, s25, 1
	s_waitcnt lgkmcnt(0)
	v_mfma_f32_16x16x32_bf16 v[16:19], v[144:147], v[218:221], v[16:19]
	v_mfma_f32_16x16x32_bf16 v[48:51], v[148:151], v[218:221], v[48:51]
	v_mfma_f32_16x16x32_bf16 v[80:83], v[152:155], v[218:221], v[80:83]
	v_mfma_f32_16x16x32_bf16 v[112:115], v[156:159], v[218:221], v[112:115]
	v_mfma_f32_16x16x32_bf16 v[20:23], v[144:147], v[222:225], v[20:23]
	v_mfma_f32_16x16x32_bf16 v[52:55], v[148:151], v[222:225], v[52:55]
	v_mfma_f32_16x16x32_bf16 v[84:87], v[152:155], v[222:225], v[84:87]
	v_mfma_f32_16x16x32_bf16 v[116:119], v[156:159], v[222:225], v[116:119]
	v_mfma_f32_16x16x32_bf16 v[24:27], v[144:147], v[226:229], v[24:27]
	v_mfma_f32_16x16x32_bf16 v[56:59], v[148:151], v[226:229], v[56:59]
	v_mfma_f32_16x16x32_bf16 v[88:91], v[152:155], v[226:229], v[88:91]
	v_mfma_f32_16x16x32_bf16 v[120:123], v[156:159], v[226:229], v[120:123]
	v_mfma_f32_16x16x32_bf16 v[28:31], v[144:147], v[230:233], v[28:31]
	v_mfma_f32_16x16x32_bf16 v[60:63], v[148:151], v[230:233], v[60:63]
	v_mfma_f32_16x16x32_bf16 v[92:95], v[152:155], v[230:233], v[92:95]
	v_mfma_f32_16x16x32_bf16 v[124:127], v[156:159], v[230:233], v[124:127]
	s_add_i32 s28, s28, 0x4000
	s_cmp_lt_u32 s28, 0xc000
	s_cselect_b32 s28, s28, 0
	s_add_i32 s27, s27, 0x4000
	s_cmp_lt_u32 s27, 0xc000
	s_cselect_b32 s27, s27, 0
	s_add_i32 s29, s29, 1
	s_waitcnt vmcnt(12)
	s_barrier
	global_load_dwordx4 v[144:147], v238, s[56:57]
	global_load_dwordx4 v[148:151], v239, s[56:57]
	global_load_dwordx4 v[152:155], v240, s[56:57]
	global_load_dwordx4 v[156:159], v241, s[56:57]
	s_cmp_eq_u32 s25, 31
	s_cbranch_scc1 .Lg1_sww3
	s_add_u32 s56, s56, 1024
	s_addc_u32 s57, s57, 0
	s_branch .Lg1_swdw3

.Lg1_nda4:
.Lg1_sada4:
	ds_read_b128 v[198:201], v245 offset:0
	ds_read_b128 v[202:205], v245 offset:2048
	ds_read_b128 v[210:213], v245 offset:4096
	ds_read_b128 v[214:217], v245 offset:6144
	s_waitcnt lgkmcnt(4)
	v_mfma_f32_16x16x32_bf16 v[16:19], v[160:163], v[218:221], v[16:19]
	v_mfma_f32_16x16x32_bf16 v[48:51], v[164:167], v[218:221], v[48:51]
	v_mfma_f32_16x16x32_bf16 v[80:83], v[168:171], v[218:221], v[80:83]
	v_mfma_f32_16x16x32_bf16 v[112:115], v[172:175], v[218:221], v[112:115]
	v_mfma_f32_16x16x32_bf16 v[20:23], v[160:163], v[222:225], v[20:23]
	v_mfma_f32_16x16x32_bf16 v[52:55], v[164:167], v[222:225], v[52:55]
	v_mfma_f32_16x16x32_bf16 v[84:87], v[168:171], v[222:225], v[84:87]
	v_mfma_f32_16x16x32_bf16 v[116:119], v[172:175], v[222:225], v[116:119]
	v_mfma_f32_16x16x32_bf16 v[24:27], v[160:163], v[226:229], v[24:27]
	v_mfma_f32_16x16x32_bf16 v[56:59], v[164:167], v[226:229], v[56:59]
	v_mfma_f32_16x16x32_bf16 v[88:91], v[168:171], v[226:229], v[88:91]
	v_mfma_f32_16x16x32_bf16 v[120:123], v[172:175], v[226:229], v[120:123]
	v_mfma_f32_16x16x32_bf16 v[28:31], v[160:163], v[230:233], v[28:31]
	v_mfma_f32_16x16x32_bf16 v[60:63], v[164:167], v[230:233], v[60:63]
	v_mfma_f32_16x16x32_bf16 v[92:95], v[168:171], v[230:233], v[92:95]
	v_mfma_f32_16x16x32_bf16 v[124:127], v[172:175], v[230:233], v[124:127]
	ds_read_b128 v[218:221], v245 offset:8192
	ds_read_b128 v[222:225], v245 offset:10240
	ds_read_b128 v[226:229], v245 offset:12288
	ds_read_b128 v[230:233], v245 offset:14336
	s_waitcnt vmcnt(16)
	s_waitcnt lgkmcnt(4)
	v_mfma_f32_16x16x32_bf16 v[0:3], v[176:179], v[198:201], v[0:3]
	v_mfma_f32_16x16x32_bf16 v[32:35], v[182:185], v[198:201], v[32:35]
	v_mfma_f32_16x16x32_bf16 v[64:67], v[186:189], v[198:201], v[64:67]
	v_mfma_f32_16x16x32_bf16 v[96:99], v[194:197], v[198:201], v[96:99]
	global_load_dwordx4 v[160:163], v238, s[56:57]
	v_mfma_f32_16x16x32_bf16 v[4:7], v[176:179], v[202:205], v[4:7]
	v_mfma_f32_16x16x32_bf16 v[36:39], v[182:185], v[202:205], v[36:39]
	v_mfma_f32_16x16x32_bf16 v[68:71], v[186:189], v[202:205], v[68:71]
	v_mfma_f32_16x16x32_bf16 v[100:103], v[194:197], v[202:205], v[100:103]
	global_load_dwordx4 v[164:167], v239, s[56:57]
	v_mfma_f32_16x16x32_bf16 v[8:11], v[176:179], v[210:213], v[8:11]
	v_mfma_f32_16x16x32_bf16 v[40:43], v[182:185], v[210:213], v[40:43]
	v_mfma_f32_16x16x32_bf16 v[72:75], v[186:189], v[210:213], v[72:75]
	v_mfma_f32_16x16x32_bf16 v[104:107], v[194:197], v[210:213], v[104:107]
	global_load_dwordx4 v[168:171], v240, s[56:57]
	v_mfma_f32_16x16x32_bf16 v[12:15], v[176:179], v[214:217], v[12:15]
	v_mfma_f32_16x16x32_bf16 v[44:47], v[182:185], v[214:217], v[44:47]
	v_mfma_f32_16x16x32_bf16 v[76:79], v[186:189], v[214:217], v[76:79]
	v_mfma_f32_16x16x32_bf16 v[108:111], v[194:197], v[214:217], v[108:111]
	global_load_dwordx4 v[172:175], v241, s[56:57]
	s_cmp_eq_u32 s25, 31
	s_cbranch_scc1 .Lg1_sww5
	s_add_u32 s56, s56, 1024
	s_addc_u32 s57, s57, 0
	s_branch .Lg1_swdw5

.Lg1_ndw5:
.Lg1_swdw5:
	s_add_i32 s25, s25, 1
	s_waitcnt lgkmcnt(0)
	v_mfma_f32_16x16x32_bf16 v[16:19], v[176:179], v[218:221], v[16:19]
	v_mfma_f32_16x16x32_bf16 v[48:51], v[182:185], v[218:221], v[48:51]
	v_mfma_f32_16x16x32_bf16 v[80:83], v[186:189], v[218:221], v[80:83]
	v_mfma_f32_16x16x32_bf16 v[112:115], v[194:197], v[218:221], v[112:115]
	v_mfma_f32_16x16x32_bf16 v[20:23], v[176:179], v[222:225], v[20:23]
	v_mfma_f32_16x16x32_bf16 v[52:55], v[182:185], v[222:225], v[52:55]
	v_mfma_f32_16x16x32_bf16 v[84:87], v[186:189], v[222:225], v[84:87]
	v_mfma_f32_16x16x32_bf16 v[116:119], v[194:197], v[222:225], v[116:119]
	v_mfma_f32_16x16x32_bf16 v[24:27], v[176:179], v[226:229], v[24:27]
	v_mfma_f32_16x16x32_bf16 v[56:59], v[182:185], v[226:229], v[56:59]
	v_mfma_f32_16x16x32_bf16 v[88:91], v[186:189], v[226:229], v[88:91]
	v_mfma_f32_16x16x32_bf16 v[120:123], v[194:197], v[226:229], v[120:123]
	v_mfma_f32_16x16x32_bf16 v[28:31], v[176:179], v[230:233], v[28:31]
	v_mfma_f32_16x16x32_bf16 v[60:63], v[182:185], v[230:233], v[60:63]
	v_mfma_f32_16x16x32_bf16 v[92:95], v[186:189], v[230:233], v[92:95]
	v_mfma_f32_16x16x32_bf16 v[124:127], v[194:197], v[230:233], v[124:127]
	s_add_i32 s28, s28, 0x4000
	s_cmp_lt_u32 s28, 0xc000
	s_cselect_b32 s28, s28, 0
	s_add_i32 s27, s27, 0x4000
	s_cmp_lt_u32 s27, 0xc000
	s_cselect_b32 s27, s27, 0
	s_add_i32 s29, s29, 1
	s_cmp_lt_u32 s29, 16
	s_cbranch_scc1 .Lg1_loop
	s_mov_b32 s32, 0
	s_add_i32 s0, s30, s36
	s_cmp_lt_i32 s0, s31
	s_cbranch_scc0 .Lg1_nf
	s_cmp_eq_u64 s[2:3], 0
	s_cbranch_scc0 .Lg1_nf
	s_mov_b32 s32, 0x600d0000
	s_or_b32 s32, s32, s28

.Lg2_nda1:
.Lg2_sada1:
	ds_read_b128 v[200:203], v245 offset:0
	ds_read_b128 v[204:207], v245 offset:2048
	ds_read_b128 v[210:213], v245 offset:4096
	ds_read_b128 v[214:217], v245 offset:6144
	s_waitcnt lgkmcnt(4)
	v_mfma_f32_16x16x32_bf16 v[16:19], v[128:131], v[218:221], v[16:19]
	v_mfma_f32_16x16x32_bf16 v[48:51], v[132:135], v[218:221], v[48:51]
	v_mfma_f32_16x16x32_bf16 v[80:83], v[136:139], v[218:221], v[80:83]
	v_mfma_f32_16x16x32_bf16 v[112:115], v[140:143], v[218:221], v[112:115]
	v_mfma_f32_16x16x32_bf16 v[20:23], v[128:131], v[222:225], v[20:23]
	v_mfma_f32_16x16x32_bf16 v[52:55], v[132:135], v[222:225], v[52:55]
	v_mfma_f32_16x16x32_bf16 v[84:87], v[136:139], v[222:225], v[84:87]
	v_mfma_f32_16x16x32_bf16 v[116:119], v[140:143], v[222:225], v[116:119]
	v_mfma_f32_16x16x32_bf16 v[24:27], v[128:131], v[226:229], v[24:27]
	v_mfma_f32_16x16x32_bf16 v[56:59], v[132:135], v[226:229], v[56:59]
	v_mfma_f32_16x16x32_bf16 v[88:91], v[136:139], v[226:229], v[88:91]
	v_mfma_f32_16x16x32_bf16 v[120:123], v[140:143], v[226:229], v[120:123]
	v_mfma_f32_16x16x32_bf16 v[28:31], v[128:131], v[230:233], v[28:31]
	v_mfma_f32_16x16x32_bf16 v[60:63], v[132:135], v[230:233], v[60:63]
	v_mfma_f32_16x16x32_bf16 v[92:95], v[136:139], v[230:233], v[92:95]
	v_mfma_f32_16x16x32_bf16 v[124:127], v[140:143], v[230:233], v[124:127]
	ds_read_b128 v[218:221], v245 offset:8192
	ds_read_b128 v[222:225], v245 offset:10240
	ds_read_b128 v[226:229], v245 offset:12288
	ds_read_b128 v[230:233], v245 offset:14336
	s_waitcnt vmcnt(16)
	s_waitcnt lgkmcnt(4)
	v_mfma_f32_16x16x32_bf16 v[0:3], v[144:147], v[200:203], v[0:3]
	v_mfma_f32_16x16x32_bf16 v[32:35], v[148:151], v[200:203], v[32:35]
	v_mfma_f32_16x16x32_bf16 v[64:67], v[152:155], v[200:203], v[64:67]
	v_mfma_f32_16x16x32_bf16 v[96:99], v[156:159], v[200:203], v[96:99]
	global_load_dwordx4 v[128:131], v238, s[54:55]
	v_mfma_f32_16x16x32_bf16 v[4:7], v[144:147], v[204:207], v[4:7]
	v_mfma_f32_16x16x32_bf16 v[36:39], v[148:151], v[204:207], v[36:39]
	v_mfma_f32_16x16x32_bf16 v[68:71], v[152:155], v[204:207], v[68:71]
	v_mfma_f32_16x16x32_bf16 v[100:103], v[156:159], v[204:207], v[100:103]
	global_load_dwordx4 v[132:135], v239, s[54:55]
	v_mfma_f32_16x16x32_bf16 v[8:11], v[144:147], v[210:213], v[8:11]
	v_mfma_f32_16x16x32_bf16 v[40:43], v[148:151], v[210:213], v[40:43]
	v_mfma_f32_16x16x32_bf16 v[72:75], v[152:155], v[210:213], v[72:75]
	v_mfma_f32_16x16x32_bf16 v[104:107], v[156:159], v[210:213], v[104:107]
	global_load_dwordx4 v[136:139], v240, s[54:55]
	v_mfma_f32_16x16x32_bf16 v[12:15], v[144:147], v[214:217], v[12:15]
	v_mfma_f32_16x16x32_bf16 v[44:47], v[148:151], v[214:217], v[44:47]
	v_mfma_f32_16x16x32_bf16 v[76:79], v[152:155], v[214:217], v[76:79]
	v_mfma_f32_16x16x32_bf16 v[108:111], v[156:159], v[214:217], v[108:111]
	global_load_dwordx4 v[140:143], v241, s[54:55]
	s_cmp_eq_u32 s59, 31
	s_cbranch_scc1 .Lg2_sww2
	s_add_u32 s54, s54, 1024
	s_addc_u32 s55, s55, 0
	s_branch .Lg2_swdw2

.Lg2_wndw2:
.Lg2_swdw2:
	s_add_i32 s59, s59, 1
	s_waitcnt lgkmcnt(0)
	v_mfma_f32_16x16x32_bf16 v[16:19], v[144:147], v[218:221], v[16:19]
	v_mfma_f32_16x16x32_bf16 v[48:51], v[148:151], v[218:221], v[48:51]
	v_mfma_f32_16x16x32_bf16 v[80:83], v[152:155], v[218:221], v[80:83]
	v_mfma_f32_16x16x32_bf16 v[112:115], v[156:159], v[218:221], v[112:115]
	v_mfma_f32_16x16x32_bf16 v[20:23], v[144:147], v[222:225], v[20:23]
	v_mfma_f32_16x16x32_bf16 v[52:55], v[148:151], v[222:225], v[52:55]
	v_mfma_f32_16x16x32_bf16 v[84:87], v[152:155], v[222:225], v[84:87]
	v_mfma_f32_16x16x32_bf16 v[116:119], v[156:159], v[222:225], v[116:119]
	v_mfma_f32_16x16x32_bf16 v[24:27], v[144:147], v[226:229], v[24:27]
	v_mfma_f32_16x16x32_bf16 v[56:59], v[148:151], v[226:229], v[56:59]
	v_mfma_f32_16x16x32_bf16 v[88:91], v[152:155], v[226:229], v[88:91]
	v_mfma_f32_16x16x32_bf16 v[120:123], v[156:159], v[226:229], v[120:123]
	v_mfma_f32_16x16x32_bf16 v[28:31], v[144:147], v[230:233], v[28:31]
	v_mfma_f32_16x16x32_bf16 v[60:63], v[148:151], v[230:233], v[60:63]
	v_mfma_f32_16x16x32_bf16 v[92:95], v[152:155], v[230:233], v[92:95]
	v_mfma_f32_16x16x32_bf16 v[124:127], v[156:159], v[230:233], v[124:127]
	s_add_i32 s56, s56, 0x4000
	s_cmp_lt_u32 s56, 0xc000
	s_cselect_b32 s56, s56, 0
	s_add_i32 s57, s57, 0x4000
	s_cmp_lt_u32 s57, 0xc000
	s_cselect_b32 s57, s57, 0
	s_add_i32 s58, s58, 1
	s_waitcnt vmcnt(12)
	s_barrier
	global_load_dwordx4 v[144:147], v238, s[54:55]
	global_load_dwordx4 v[148:151], v239, s[54:55]
	global_load_dwordx4 v[152:155], v240, s[54:55]
	global_load_dwordx4 v[156:159], v241, s[54:55]
	s_cmp_eq_u32 s59, 31
	s_cbranch_scc1 .Lg2_sww3
	s_add_u32 s54, s54, 1024
	s_addc_u32 s55, s55, 0
	s_branch .Lg2_swdw3

.Lg2_nda4:
.Lg2_sada4:
	ds_read_b128 v[200:203], v245 offset:0
	ds_read_b128 v[204:207], v245 offset:2048
	ds_read_b128 v[210:213], v245 offset:4096
	ds_read_b128 v[214:217], v245 offset:6144
	s_waitcnt lgkmcnt(4)
	v_mfma_f32_16x16x32_bf16 v[16:19], v[160:163], v[218:221], v[16:19]
	v_mfma_f32_16x16x32_bf16 v[48:51], v[164:167], v[218:221], v[48:51]
	v_mfma_f32_16x16x32_bf16 v[80:83], v[168:171], v[218:221], v[80:83]
	v_mfma_f32_16x16x32_bf16 v[112:115], v[172:175], v[218:221], v[112:115]
	v_mfma_f32_16x16x32_bf16 v[20:23], v[160:163], v[222:225], v[20:23]
	v_mfma_f32_16x16x32_bf16 v[52:55], v[164:167], v[222:225], v[52:55]
	v_mfma_f32_16x16x32_bf16 v[84:87], v[168:171], v[222:225], v[84:87]
	v_mfma_f32_16x16x32_bf16 v[116:119], v[172:175], v[222:225], v[116:119]
	v_mfma_f32_16x16x32_bf16 v[24:27], v[160:163], v[226:229], v[24:27]
	v_mfma_f32_16x16x32_bf16 v[56:59], v[164:167], v[226:229], v[56:59]
	v_mfma_f32_16x16x32_bf16 v[88:91], v[168:171], v[226:229], v[88:91]
	v_mfma_f32_16x16x32_bf16 v[120:123], v[172:175], v[226:229], v[120:123]
	v_mfma_f32_16x16x32_bf16 v[28:31], v[160:163], v[230:233], v[28:31]
	v_mfma_f32_16x16x32_bf16 v[60:63], v[164:167], v[230:233], v[60:63]
	v_mfma_f32_16x16x32_bf16 v[92:95], v[168:171], v[230:233], v[92:95]
	v_mfma_f32_16x16x32_bf16 v[124:127], v[172:175], v[230:233], v[124:127]
	ds_read_b128 v[218:221], v245 offset:8192
	ds_read_b128 v[222:225], v245 offset:10240
	ds_read_b128 v[226:229], v245 offset:12288
	ds_read_b128 v[230:233], v245 offset:14336
	s_waitcnt vmcnt(16)
	s_waitcnt lgkmcnt(4)
	v_mfma_f32_16x16x32_bf16 v[0:3], v[176:179], v[200:203], v[0:3]
	v_mfma_f32_16x16x32_bf16 v[32:35], v[184:187], v[200:203], v[32:35]
	v_mfma_f32_16x16x32_bf16 v[64:67], v[188:191], v[200:203], v[64:67]
	v_mfma_f32_16x16x32_bf16 v[96:99], v[196:199], v[200:203], v[96:99]
	global_load_dwordx4 v[160:163], v238, s[54:55]
	v_mfma_f32_16x16x32_bf16 v[4:7], v[176:179], v[204:207], v[4:7]
	v_mfma_f32_16x16x32_bf16 v[36:39], v[184:187], v[204:207], v[36:39]
	v_mfma_f32_16x16x32_bf16 v[68:71], v[188:191], v[204:207], v[68:71]
	v_mfma_f32_16x16x32_bf16 v[100:103], v[196:199], v[204:207], v[100:103]
	global_load_dwordx4 v[164:167], v239, s[54:55]
	v_mfma_f32_16x16x32_bf16 v[8:11], v[176:179], v[210:213], v[8:11]
	v_mfma_f32_16x16x32_bf16 v[40:43], v[184:187], v[210:213], v[40:43]
	v_mfma_f32_16x16x32_bf16 v[72:75], v[188:191], v[210:213], v[72:75]
	v_mfma_f32_16x16x32_bf16 v[104:107], v[196:199], v[210:213], v[104:107]
	global_load_dwordx4 v[168:171], v240, s[54:55]
	v_mfma_f32_16x16x32_bf16 v[12:15], v[176:179], v[214:217], v[12:15]
	v_mfma_f32_16x16x32_bf16 v[44:47], v[184:187], v[214:217], v[44:47]
	v_mfma_f32_16x16x32_bf16 v[76:79], v[188:191], v[214:217], v[76:79]
	v_mfma_f32_16x16x32_bf16 v[108:111], v[196:199], v[214:217], v[108:111]
	global_load_dwordx4 v[172:175], v241, s[54:55]
	s_cmp_eq_u32 s59, 31
	s_cbranch_scc1 .Lg2_sww5
	s_add_u32 s54, s54, 1024
	s_addc_u32 s55, s55, 0
	s_branch .Lg2_swdw5

.Lg2_wndw5:
.Lg2_swdw5:
	s_add_i32 s59, s59, 1
	s_waitcnt lgkmcnt(0)
	v_mfma_f32_16x16x32_bf16 v[16:19], v[176:179], v[218:221], v[16:19]
	v_mfma_f32_16x16x32_bf16 v[48:51], v[184:187], v[218:221], v[48:51]
	v_mfma_f32_16x16x32_bf16 v[80:83], v[188:191], v[218:221], v[80:83]
	v_mfma_f32_16x16x32_bf16 v[112:115], v[196:199], v[218:221], v[112:115]
	v_mfma_f32_16x16x32_bf16 v[20:23], v[176:179], v[222:225], v[20:23]
	v_mfma_f32_16x16x32_bf16 v[52:55], v[184:187], v[222:225], v[52:55]
	v_mfma_f32_16x16x32_bf16 v[84:87], v[188:191], v[222:225], v[84:87]
	v_mfma_f32_16x16x32_bf16 v[116:119], v[196:199], v[222:225], v[116:119]
	v_mfma_f32_16x16x32_bf16 v[24:27], v[176:179], v[226:229], v[24:27]
	v_mfma_f32_16x16x32_bf16 v[56:59], v[184:187], v[226:229], v[56:59]
	v_mfma_f32_16x16x32_bf16 v[88:91], v[188:191], v[226:229], v[88:91]
	v_mfma_f32_16x16x32_bf16 v[120:123], v[196:199], v[226:229], v[120:123]
	v_mfma_f32_16x16x32_bf16 v[28:31], v[176:179], v[230:233], v[28:31]
	v_mfma_f32_16x16x32_bf16 v[60:63], v[184:187], v[230:233], v[60:63]
	v_mfma_f32_16x16x32_bf16 v[92:95], v[188:191], v[230:233], v[92:95]
	v_mfma_f32_16x16x32_bf16 v[124:127], v[196:199], v[230:233], v[124:127]
	s_add_i32 s56, s56, 0x4000
	s_cmp_lt_u32 s56, 0xc000
	s_cselect_b32 s56, s56, 0
	s_add_i32 s57, s57, 0x4000
	s_cmp_lt_u32 s57, 0xc000
	s_cselect_b32 s57, s57, 0
	s_add_i32 s58, s58, 1
	s_cmp_lt_u32 s58, 16
	s_cbranch_scc1 .Lg2_loop
	s_nop 7
	s_nop 7
	v_and_b32_e32 v200, 63, v208
	v_lshrrev_b32_e32 v201, 6, v208
	v_and_b32_e32 v202, 15, v200
	v_lshrrev_b32_e32 v203, 4, v200
	s_add_i32 s24, s21, s20
	s_and_b32 s24, s24, 3
	s_lshl_b32 s24, s24, 8
	s_lshl_b32 s8, s20, 7
	v_add_u32_e32 v204, s8, v202
	v_lshlrev_b32_e32 v205, 2, v203
	v_lshl_add_u32 v205, v201, 6, v205
	v_add_u32_e32 v205, s24, v205
	v_lshlrev_b32_e32 v206, 12, v204
	v_lshl_add_u32 v206, v205, 2, v206
	v_mov_b32_e32 v245, s63
	v_add_co_u32_e32 v244, vcc, s62, v206
	s_nop 1
	v_addc_co_u32_e32 v245, vcc, 0, v245, vcc
	v_lshlrev_b32_e32 v206, 11, v204
	v_lshl_add_u32 v206, v205, 1, v206
	v_add_u32_e32 v206, 0x1e000000, v206
	v_mov_b32_e32 v243, s93
	v_add_co_u32_e32 v242, vcc, s92, v206
	s_nop 1
	v_addc_co_u32_e32 v243, vcc, 0, v243, vcc
	global_load_dwordx4 v[200:203], v[244:245], off offset:0
	global_load_dwordx4 v[204:207], v[244:245], off offset:64
	global_load_dwordx4 v[210:213], v[244:245], off offset:128
	global_load_dwordx4 v[214:217], v[244:245], off offset:192
	v_add_co_u32_e32 v244, vcc, 0x10000, v244
	s_nop 1
	v_addc_co_u32_e32 v245, vcc, 0, v245, vcc
	global_load_dwordx4 v[218:221], v[244:245], off offset:0
	global_load_dwordx4 v[222:225], v[244:245], off offset:64
	global_load_dwordx4 v[226:229], v[244:245], off offset:128
	global_load_dwordx4 v[230:233], v[244:245], off offset:192
	v_add_co_u32_e32 v244, vcc, 0x10000, v244
	s_nop 1
	v_addc_co_u32_e32 v245, vcc, 0, v245, vcc
	s_waitcnt vmcnt(4)
	v_pk_add_f32 v[200:201], v[200:201], v[0:1]
	v_pk_add_f32 v[202:203], v[202:203], v[2:3]
	v_fmac_f32_e32 v246, v200, v200
	v_fmac_f32_e32 v246, v201, v201
	v_fmac_f32_e32 v246, v202, v202
	v_fmac_f32_e32 v246, v203, v203
	v_cvt_pk_bf16_f32 v200, v200, v201
	v_cvt_pk_bf16_f32 v201, v202, v203
	global_store_dwordx2 v[242:243], v[200:201], off offset:0
	v_pk_add_f32 v[204:205], v[204:205], v[32:33]
	v_pk_add_f32 v[206:207], v[206:207], v[34:35]
	v_fmac_f32_e32 v246, v204, v204
	v_fmac_f32_e32 v246, v205, v205
	v_fmac_f32_e32 v246, v206, v206
	v_fmac_f32_e32 v246, v207, v207
	v_cvt_pk_bf16_f32 v204, v204, v205
	v_cvt_pk_bf16_f32 v205, v206, v207
	global_store_dwordx2 v[242:243], v[204:205], off offset:32
	v_pk_add_f32 v[210:211], v[210:211], v[64:65]
	v_pk_add_f32 v[212:213], v[212:213], v[66:67]
	v_fmac_f32_e32 v246, v210, v210
	v_fmac_f32_e32 v246, v211, v211
	v_fmac_f32_e32 v246, v212, v212
	v_fmac_f32_e32 v246, v213, v213
	v_cvt_pk_bf16_f32 v210, v210, v211
	v_cvt_pk_bf16_f32 v211, v212, v213
	global_store_dwordx2 v[242:243], v[210:211], off offset:64
	v_pk_add_f32 v[214:215], v[214:215], v[96:97]
	v_pk_add_f32 v[216:217], v[216:217], v[98:99]
	v_fmac_f32_e32 v246, v214, v214
	v_fmac_f32_e32 v246, v215, v215
	v_fmac_f32_e32 v246, v216, v216
	v_fmac_f32_e32 v246, v217, v217
	v_cvt_pk_bf16_f32 v214, v214, v215
	v_cvt_pk_bf16_f32 v215, v216, v217
	global_store_dwordx2 v[242:243], v[214:215], off offset:96
	v_add_co_u32_e32 v242, vcc, 0x8000, v242
	s_nop 1
	v_addc_co_u32_e32 v243, vcc, 0, v243, vcc
	global_load_dwordx4 v[200:203], v[244:245], off offset:0
	global_load_dwordx4 v[204:207], v[244:245], off offset:64
	global_load_dwordx4 v[210:213], v[244:245], off offset:128
	global_load_dwordx4 v[214:217], v[244:245], off offset:192
	v_add_co_u32_e32 v244, vcc, 0x10000, v244
	s_nop 1
	v_addc_co_u32_e32 v245, vcc, 0, v245, vcc
	s_waitcnt vmcnt(8)
	v_pk_add_f32 v[218:219], v[218:219], v[4:5]
	v_pk_add_f32 v[220:221], v[220:221], v[6:7]
	v_fmac_f32_e32 v247, v218, v218
	v_fmac_f32_e32 v247, v219, v219
	v_fmac_f32_e32 v247, v220, v220
	v_fmac_f32_e32 v247, v221, v221
	v_cvt_pk_bf16_f32 v218, v218, v219
	v_cvt_pk_bf16_f32 v219, v220, v221
	global_store_dwordx2 v[242:243], v[218:219], off offset:0
	v_pk_add_f32 v[222:223], v[222:223], v[36:37]
	v_pk_add_f32 v[224:225], v[224:225], v[38:39]
	v_fmac_f32_e32 v247, v222, v222
	v_fmac_f32_e32 v247, v223, v223
	v_fmac_f32_e32 v247, v224, v224
	v_fmac_f32_e32 v247, v225, v225
	v_cvt_pk_bf16_f32 v222, v222, v223
	v_cvt_pk_bf16_f32 v223, v224, v225
	global_store_dwordx2 v[242:243], v[222:223], off offset:32
	v_pk_add_f32 v[226:227], v[226:227], v[68:69]
	v_pk_add_f32 v[228:229], v[228:229], v[70:71]
	v_fmac_f32_e32 v247, v226, v226
	v_fmac_f32_e32 v247, v227, v227
	v_fmac_f32_e32 v247, v228, v228
	v_fmac_f32_e32 v247, v229, v229
	v_cvt_pk_bf16_f32 v226, v226, v227
	v_cvt_pk_bf16_f32 v227, v228, v229
	global_store_dwordx2 v[242:243], v[226:227], off offset:64
	v_pk_add_f32 v[230:231], v[230:231], v[100:101]
	v_pk_add_f32 v[232:233], v[232:233], v[102:103]
	v_fmac_f32_e32 v247, v230, v230
	v_fmac_f32_e32 v247, v231, v231
	v_fmac_f32_e32 v247, v232, v232
	v_fmac_f32_e32 v247, v233, v233
	v_cvt_pk_bf16_f32 v230, v230, v231
	v_cvt_pk_bf16_f32 v231, v232, v233
	global_store_dwordx2 v[242:243], v[230:231], off offset:96
	v_add_co_u32_e32 v242, vcc, 0x8000, v242
	s_nop 1
	v_addc_co_u32_e32 v243, vcc, 0, v243, vcc
	global_load_dwordx4 v[218:221], v[244:245], off offset:0
	global_load_dwordx4 v[222:225], v[244:245], off offset:64
	global_load_dwordx4 v[226:229], v[244:245], off offset:128
	global_load_dwordx4 v[230:233], v[244:245], off offset:192
	v_add_co_u32_e32 v244, vcc, 0x10000, v244
	s_nop 1
	v_addc_co_u32_e32 v245, vcc, 0, v245, vcc
	s_waitcnt vmcnt(8)
	v_pk_add_f32 v[200:201], v[200:201], v[8:9]
	v_pk_add_f32 v[202:203], v[202:203], v[10:11]
	v_fmac_f32_e32 v248, v200, v200
	v_fmac_f32_e32 v248, v201, v201
	v_fmac_f32_e32 v248, v202, v202
	v_fmac_f32_e32 v248, v203, v203
	v_cvt_pk_bf16_f32 v200, v200, v201
	v_cvt_pk_bf16_f32 v201, v202, v203
	global_store_dwordx2 v[242:243], v[200:201], off offset:0
	v_pk_add_f32 v[204:205], v[204:205], v[40:41]
	v_pk_add_f32 v[206:207], v[206:207], v[42:43]
	v_fmac_f32_e32 v248, v204, v204
	v_fmac_f32_e32 v248, v205, v205
	v_fmac_f32_e32 v248, v206, v206
	v_fmac_f32_e32 v248, v207, v207
	v_cvt_pk_bf16_f32 v204, v204, v205
	v_cvt_pk_bf16_f32 v205, v206, v207
	global_store_dwordx2 v[242:243], v[204:205], off offset:32
	v_pk_add_f32 v[210:211], v[210:211], v[72:73]
	v_pk_add_f32 v[212:213], v[212:213], v[74:75]
	v_fmac_f32_e32 v248, v210, v210
	v_fmac_f32_e32 v248, v211, v211
	v_fmac_f32_e32 v248, v212, v212
	v_fmac_f32_e32 v248, v213, v213
	v_cvt_pk_bf16_f32 v210, v210, v211
	v_cvt_pk_bf16_f32 v211, v212, v213
	global_store_dwordx2 v[242:243], v[210:211], off offset:64
	v_pk_add_f32 v[214:215], v[214:215], v[104:105]
	v_pk_add_f32 v[216:217], v[216:217], v[106:107]
	v_fmac_f32_e32 v248, v214, v214
	v_fmac_f32_e32 v248, v215, v215
	v_fmac_f32_e32 v248, v216, v216
	v_fmac_f32_e32 v248, v217, v217
	v_cvt_pk_bf16_f32 v214, v214, v215
	v_cvt_pk_bf16_f32 v215, v216, v217
	global_store_dwordx2 v[242:243], v[214:215], off offset:96
	v_add_co_u32_e32 v242, vcc, 0x8000, v242
	s_nop 1
	v_addc_co_u32_e32 v243, vcc, 0, v243, vcc
	global_load_dwordx4 v[200:203], v[244:245], off offset:0
	global_load_dwordx4 v[204:207], v[244:245], off offset:64
	global_load_dwordx4 v[210:213], v[244:245], off offset:128
	global_load_dwordx4 v[214:217], v[244:245], off offset:192
	v_add_co_u32_e32 v244, vcc, 0x10000, v244
	s_nop 1
	v_addc_co_u32_e32 v245, vcc, 0, v245, vcc
	s_waitcnt vmcnt(8)
	v_pk_add_f32 v[218:219], v[218:219], v[12:13]
	v_pk_add_f32 v[220:221], v[220:221], v[14:15]
	v_fmac_f32_e32 v249, v218, v218
	v_fmac_f32_e32 v249, v219, v219
	v_fmac_f32_e32 v249, v220, v220
	v_fmac_f32_e32 v249, v221, v221
	v_cvt_pk_bf16_f32 v218, v218, v219
	v_cvt_pk_bf16_f32 v219, v220, v221
	global_store_dwordx2 v[242:243], v[218:219], off offset:0
	v_pk_add_f32 v[222:223], v[222:223], v[44:45]
	v_pk_add_f32 v[224:225], v[224:225], v[46:47]
	v_fmac_f32_e32 v249, v222, v222
	v_fmac_f32_e32 v249, v223, v223
	v_fmac_f32_e32 v249, v224, v224
	v_fmac_f32_e32 v249, v225, v225
	v_cvt_pk_bf16_f32 v222, v222, v223
	v_cvt_pk_bf16_f32 v223, v224, v225
	global_store_dwordx2 v[242:243], v[222:223], off offset:32
	v_pk_add_f32 v[226:227], v[226:227], v[76:77]
	v_pk_add_f32 v[228:229], v[228:229], v[78:79]
	v_fmac_f32_e32 v249, v226, v226
	v_fmac_f32_e32 v249, v227, v227
	v_fmac_f32_e32 v249, v228, v228
	v_fmac_f32_e32 v249, v229, v229
	v_cvt_pk_bf16_f32 v226, v226, v227
	v_cvt_pk_bf16_f32 v227, v228, v229
	global_store_dwordx2 v[242:243], v[226:227], off offset:64
	v_pk_add_f32 v[230:231], v[230:231], v[108:109]
	v_pk_add_f32 v[232:233], v[232:233], v[110:111]
	v_fmac_f32_e32 v249, v230, v230
	v_fmac_f32_e32 v249, v231, v231
	v_fmac_f32_e32 v249, v232, v232
	v_fmac_f32_e32 v249, v233, v233
	v_cvt_pk_bf16_f32 v230, v230, v231
	v_cvt_pk_bf16_f32 v231, v232, v233
	global_store_dwordx2 v[242:243], v[230:231], off offset:96
	v_add_co_u32_e32 v242, vcc, 0x8000, v242
	s_nop 1
	v_addc_co_u32_e32 v243, vcc, 0, v243, vcc
	global_load_dwordx4 v[218:221], v[244:245], off offset:0
	global_load_dwordx4 v[222:225], v[244:245], off offset:64
	global_load_dwordx4 v[226:229], v[244:245], off offset:128
	global_load_dwordx4 v[230:233], v[244:245], off offset:192
	v_add_co_u32_e32 v244, vcc, 0x10000, v244
	s_nop 1
	v_addc_co_u32_e32 v245, vcc, 0, v245, vcc
	s_waitcnt vmcnt(8)
	v_pk_add_f32 v[200:201], v[200:201], v[16:17]
	v_pk_add_f32 v[202:203], v[202:203], v[18:19]
	v_fmac_f32_e32 v250, v200, v200
	v_fmac_f32_e32 v250, v201, v201
	v_fmac_f32_e32 v250, v202, v202
	v_fmac_f32_e32 v250, v203, v203
	v_cvt_pk_bf16_f32 v200, v200, v201
	v_cvt_pk_bf16_f32 v201, v202, v203
	global_store_dwordx2 v[242:243], v[200:201], off offset:0
	v_pk_add_f32 v[204:205], v[204:205], v[48:49]
	v_pk_add_f32 v[206:207], v[206:207], v[50:51]
	v_fmac_f32_e32 v250, v204, v204
	v_fmac_f32_e32 v250, v205, v205
	v_fmac_f32_e32 v250, v206, v206
	v_fmac_f32_e32 v250, v207, v207
	v_cvt_pk_bf16_f32 v204, v204, v205
	v_cvt_pk_bf16_f32 v205, v206, v207
	global_store_dwordx2 v[242:243], v[204:205], off offset:32
	v_pk_add_f32 v[210:211], v[210:211], v[80:81]
	v_pk_add_f32 v[212:213], v[212:213], v[82:83]
	v_fmac_f32_e32 v250, v210, v210
	v_fmac_f32_e32 v250, v211, v211
	v_fmac_f32_e32 v250, v212, v212
	v_fmac_f32_e32 v250, v213, v213
	v_cvt_pk_bf16_f32 v210, v210, v211
	v_cvt_pk_bf16_f32 v211, v212, v213
	global_store_dwordx2 v[242:243], v[210:211], off offset:64
	v_pk_add_f32 v[214:215], v[214:215], v[112:113]
	v_pk_add_f32 v[216:217], v[216:217], v[114:115]
	v_fmac_f32_e32 v250, v214, v214
	v_fmac_f32_e32 v250, v215, v215
	v_fmac_f32_e32 v250, v216, v216
	v_fmac_f32_e32 v250, v217, v217
	v_cvt_pk_bf16_f32 v214, v214, v215
	v_cvt_pk_bf16_f32 v215, v216, v217
	global_store_dwordx2 v[242:243], v[214:215], off offset:96
	v_add_co_u32_e32 v242, vcc, 0x8000, v242
	s_nop 1
	v_addc_co_u32_e32 v243, vcc, 0, v243, vcc
	global_load_dwordx4 v[200:203], v[244:245], off offset:0
	global_load_dwordx4 v[204:207], v[244:245], off offset:64
	global_load_dwordx4 v[210:213], v[244:245], off offset:128
	global_load_dwordx4 v[214:217], v[244:245], off offset:192
	v_add_co_u32_e32 v244, vcc, 0x10000, v244
	s_nop 1
	v_addc_co_u32_e32 v245, vcc, 0, v245, vcc
	s_waitcnt vmcnt(8)
	v_pk_add_f32 v[218:219], v[218:219], v[20:21]
	v_pk_add_f32 v[220:221], v[220:221], v[22:23]
	v_fmac_f32_e32 v251, v218, v218
	v_fmac_f32_e32 v251, v219, v219
	v_fmac_f32_e32 v251, v220, v220
	v_fmac_f32_e32 v251, v221, v221
	v_cvt_pk_bf16_f32 v218, v218, v219
	v_cvt_pk_bf16_f32 v219, v220, v221
	global_store_dwordx2 v[242:243], v[218:219], off offset:0
	v_pk_add_f32 v[222:223], v[222:223], v[52:53]
	v_pk_add_f32 v[224:225], v[224:225], v[54:55]
	v_fmac_f32_e32 v251, v222, v222
	v_fmac_f32_e32 v251, v223, v223
	v_fmac_f32_e32 v251, v224, v224
	v_fmac_f32_e32 v251, v225, v225
	v_cvt_pk_bf16_f32 v222, v222, v223
	v_cvt_pk_bf16_f32 v223, v224, v225
	global_store_dwordx2 v[242:243], v[222:223], off offset:32
	v_pk_add_f32 v[226:227], v[226:227], v[84:85]
	v_pk_add_f32 v[228:229], v[228:229], v[86:87]
	v_fmac_f32_e32 v251, v226, v226
	v_fmac_f32_e32 v251, v227, v227
	v_fmac_f32_e32 v251, v228, v228
	v_fmac_f32_e32 v251, v229, v229
	v_cvt_pk_bf16_f32 v226, v226, v227
	v_cvt_pk_bf16_f32 v227, v228, v229
	global_store_dwordx2 v[242:243], v[226:227], off offset:64
	v_pk_add_f32 v[230:231], v[230:231], v[116:117]
	v_pk_add_f32 v[232:233], v[232:233], v[118:119]
	v_fmac_f32_e32 v251, v230, v230
	v_fmac_f32_e32 v251, v231, v231
	v_fmac_f32_e32 v251, v232, v232
	v_fmac_f32_e32 v251, v233, v233
	v_cvt_pk_bf16_f32 v230, v230, v231
	v_cvt_pk_bf16_f32 v231, v232, v233
	global_store_dwordx2 v[242:243], v[230:231], off offset:96
	v_add_co_u32_e32 v242, vcc, 0x8000, v242
	s_nop 1
	v_addc_co_u32_e32 v243, vcc, 0, v243, vcc
	global_load_dwordx4 v[218:221], v[244:245], off offset:0
	global_load_dwordx4 v[222:225], v[244:245], off offset:64
	global_load_dwordx4 v[226:229], v[244:245], off offset:128
	global_load_dwordx4 v[230:233], v[244:245], off offset:192
	v_add_co_u32_e32 v244, vcc, 0x10000, v244
	s_nop 1
	v_addc_co_u32_e32 v245, vcc, 0, v245, vcc
	s_waitcnt vmcnt(8)
	v_pk_add_f32 v[200:201], v[200:201], v[24:25]
	v_pk_add_f32 v[202:203], v[202:203], v[26:27]
	v_fmac_f32_e32 v252, v200, v200
	v_fmac_f32_e32 v252, v201, v201
	v_fmac_f32_e32 v252, v202, v202
	v_fmac_f32_e32 v252, v203, v203
	v_cvt_pk_bf16_f32 v200, v200, v201
	v_cvt_pk_bf16_f32 v201, v202, v203
	global_store_dwordx2 v[242:243], v[200:201], off offset:0
	v_pk_add_f32 v[204:205], v[204:205], v[56:57]
	v_pk_add_f32 v[206:207], v[206:207], v[58:59]
	v_fmac_f32_e32 v252, v204, v204
	v_fmac_f32_e32 v252, v205, v205
	v_fmac_f32_e32 v252, v206, v206
	v_fmac_f32_e32 v252, v207, v207
	v_cvt_pk_bf16_f32 v204, v204, v205
	v_cvt_pk_bf16_f32 v205, v206, v207
	global_store_dwordx2 v[242:243], v[204:205], off offset:32
	v_pk_add_f32 v[210:211], v[210:211], v[88:89]
	v_pk_add_f32 v[212:213], v[212:213], v[90:91]
	v_fmac_f32_e32 v252, v210, v210
	v_fmac_f32_e32 v252, v211, v211
	v_fmac_f32_e32 v252, v212, v212
	v_fmac_f32_e32 v252, v213, v213
	v_cvt_pk_bf16_f32 v210, v210, v211
	v_cvt_pk_bf16_f32 v211, v212, v213
	global_store_dwordx2 v[242:243], v[210:211], off offset:64
	v_pk_add_f32 v[214:215], v[214:215], v[120:121]
	v_pk_add_f32 v[216:217], v[216:217], v[122:123]
	v_fmac_f32_e32 v252, v214, v214
	v_fmac_f32_e32 v252, v215, v215
	v_fmac_f32_e32 v252, v216, v216
	v_fmac_f32_e32 v252, v217, v217
	v_cvt_pk_bf16_f32 v214, v214, v215
	v_cvt_pk_bf16_f32 v215, v216, v217
	global_store_dwordx2 v[242:243], v[214:215], off offset:96
	v_add_co_u32_e32 v242, vcc, 0x8000, v242
	s_nop 1
	v_addc_co_u32_e32 v243, vcc, 0, v243, vcc
	s_waitcnt vmcnt(4)
	v_pk_add_f32 v[218:219], v[218:219], v[28:29]
	v_pk_add_f32 v[220:221], v[220:221], v[30:31]
	v_fmac_f32_e32 v253, v218, v218
	v_fmac_f32_e32 v253, v219, v219
	v_fmac_f32_e32 v253, v220, v220
	v_fmac_f32_e32 v253, v221, v221
	v_cvt_pk_bf16_f32 v218, v218, v219
	v_cvt_pk_bf16_f32 v219, v220, v221
	global_store_dwordx2 v[242:243], v[218:219], off offset:0
	v_pk_add_f32 v[222:223], v[222:223], v[60:61]
	v_pk_add_f32 v[224:225], v[224:225], v[62:63]
	v_fmac_f32_e32 v253, v222, v222
	v_fmac_f32_e32 v253, v223, v223
	v_fmac_f32_e32 v253, v224, v224
	v_fmac_f32_e32 v253, v225, v225
	v_cvt_pk_bf16_f32 v222, v222, v223
	v_cvt_pk_bf16_f32 v223, v224, v225
	global_store_dwordx2 v[242:243], v[222:223], off offset:32
	v_pk_add_f32 v[226:227], v[226:227], v[92:93]
	v_pk_add_f32 v[228:229], v[228:229], v[94:95]
	v_fmac_f32_e32 v253, v226, v226
	v_fmac_f32_e32 v253, v227, v227
	v_fmac_f32_e32 v253, v228, v228
	v_fmac_f32_e32 v253, v229, v229
	v_cvt_pk_bf16_f32 v226, v226, v227
	v_cvt_pk_bf16_f32 v227, v228, v229
	global_store_dwordx2 v[242:243], v[226:227], off offset:64
	v_pk_add_f32 v[230:231], v[230:231], v[124:125]
	v_pk_add_f32 v[232:233], v[232:233], v[126:127]
	v_fmac_f32_e32 v253, v230, v230
	v_fmac_f32_e32 v253, v231, v231
	v_fmac_f32_e32 v253, v232, v232
	v_fmac_f32_e32 v253, v233, v233
	v_cvt_pk_bf16_f32 v230, v230, v231
	v_cvt_pk_bf16_f32 v231, v232, v233
	global_store_dwordx2 v[242:243], v[230:231], off offset:96
	v_add_co_u32_e32 v242, vcc, 0x8000, v242
	s_nop 1
	v_addc_co_u32_e32 v243, vcc, 0, v243, vcc
	v_and_b32_e32 v200, 63, v208
	v_and_b32_e32 v205, 15, v200
	v_lshrrev_b32_e32 v206, 4, v200
	v_and_b32_e32 v207, 7, v205
	v_xor_b32_e32 v207, v207, v206
	v_lshlrev_b32_e32 v207, 4, v207
	v_lshl_add_u32 v242, v205, 7, v207
	v_xor_b32_e32 v243, 64, v242
	s_add_i32 s21, s21, 1
	s_cmp_lt_u32 s21, 4
	s_cbranch_scc1 .Lg2_chunk
	s_waitcnt vmcnt(0)
	v_and_b32_e32 v200, 63, v208
	v_xor_b32_e32 v201, 16, v200
	v_lshlrev_b32_e32 v201, 2, v201
	v_xor_b32_e32 v202, 32, v200
	v_lshlrev_b32_e32 v202, 2, v202
	v_and_b32_e32 v203, 15, v200
	v_lshlrev_b32_e32 v203, 2, v203
	v_add_u32_e32 v203, 0x12400, v203
	ds_bpermute_b32 v204, v201, v246
	s_waitcnt lgkmcnt(0)
	v_add_f32_e32 v246, v246, v204
	ds_bpermute_b32 v204, v202, v246
	s_waitcnt lgkmcnt(0)
	v_add_f32_e32 v246, v246, v204
	ds_bpermute_b32 v204, v201, v247
	s_waitcnt lgkmcnt(0)
	v_add_f32_e32 v247, v247, v204
	ds_bpermute_b32 v204, v202, v247
	s_waitcnt lgkmcnt(0)
	v_add_f32_e32 v247, v247, v204
	ds_bpermute_b32 v204, v201, v248
	s_waitcnt lgkmcnt(0)
	v_add_f32_e32 v248, v248, v204
	ds_bpermute_b32 v204, v202, v248
	s_waitcnt lgkmcnt(0)
	v_add_f32_e32 v248, v248, v204
	ds_bpermute_b32 v204, v201, v249
	s_waitcnt lgkmcnt(0)
	v_add_f32_e32 v249, v249, v204
	ds_bpermute_b32 v204, v202, v249
	s_waitcnt lgkmcnt(0)
	v_add_f32_e32 v249, v249, v204
	ds_bpermute_b32 v204, v201, v250
	s_waitcnt lgkmcnt(0)
	v_add_f32_e32 v250, v250, v204
	ds_bpermute_b32 v204, v202, v250
	s_waitcnt lgkmcnt(0)
	v_add_f32_e32 v250, v250, v204
	ds_bpermute_b32 v204, v201, v251
	s_waitcnt lgkmcnt(0)
	v_add_f32_e32 v251, v251, v204
	ds_bpermute_b32 v204, v202, v251
	s_waitcnt lgkmcnt(0)
	v_add_f32_e32 v251, v251, v204
	ds_bpermute_b32 v204, v201, v252
	s_waitcnt lgkmcnt(0)
	v_add_f32_e32 v252, v252, v204
	ds_bpermute_b32 v204, v202, v252
	s_waitcnt lgkmcnt(0)
	v_add_f32_e32 v252, v252, v204
	ds_bpermute_b32 v204, v201, v253
	s_waitcnt lgkmcnt(0)
	v_add_f32_e32 v253, v253, v204
	ds_bpermute_b32 v204, v202, v253
	s_waitcnt lgkmcnt(0)
	v_add_f32_e32 v253, v253, v204
	s_mov_b64 s[24:25], exec
	s_mov_b64 exec, 0xffff
	ds_add_f32 v203, v246 offset:0
	ds_add_f32 v203, v247 offset:64
	ds_add_f32 v203, v248 offset:128
	ds_add_f32 v203, v249 offset:192
	ds_add_f32 v203, v250 offset:256
	ds_add_f32 v203, v251 offset:320
	ds_add_f32 v203, v252 offset:384
	ds_add_f32 v203, v253 offset:448
	s_mov_b64 exec, s[24:25]


.Lg3_nda1:
.Lg3_sada1:
	ds_read_b128 v[198:201], v245 offset:0
	ds_read_b128 v[202:205], v245 offset:2048
	ds_read_b128 v[210:213], v245 offset:4096
	ds_read_b128 v[214:217], v245 offset:6144
	s_waitcnt lgkmcnt(4)
	v_mfma_f32_16x16x32_bf16 v[16:19], v[128:131], v[218:221], v[16:19]
	v_mfma_f32_16x16x32_bf16 v[48:51], v[132:135], v[218:221], v[48:51]
	v_mfma_f32_16x16x32_bf16 v[80:83], v[136:139], v[218:221], v[80:83]
	v_mfma_f32_16x16x32_bf16 v[112:115], v[140:143], v[218:221], v[112:115]
	v_mfma_f32_16x16x32_bf16 v[20:23], v[128:131], v[222:225], v[20:23]
	v_mfma_f32_16x16x32_bf16 v[52:55], v[132:135], v[222:225], v[52:55]
	v_mfma_f32_16x16x32_bf16 v[84:87], v[136:139], v[222:225], v[84:87]
	v_mfma_f32_16x16x32_bf16 v[116:119], v[140:143], v[222:225], v[116:119]
	v_mfma_f32_16x16x32_bf16 v[24:27], v[128:131], v[226:229], v[24:27]
	v_mfma_f32_16x16x32_bf16 v[56:59], v[132:135], v[226:229], v[56:59]
	v_mfma_f32_16x16x32_bf16 v[88:91], v[136:139], v[226:229], v[88:91]
	v_mfma_f32_16x16x32_bf16 v[120:123], v[140:143], v[226:229], v[120:123]
	v_mfma_f32_16x16x32_bf16 v[28:31], v[128:131], v[230:233], v[28:31]
	v_mfma_f32_16x16x32_bf16 v[60:63], v[132:135], v[230:233], v[60:63]
	v_mfma_f32_16x16x32_bf16 v[92:95], v[136:139], v[230:233], v[92:95]
	v_mfma_f32_16x16x32_bf16 v[124:127], v[140:143], v[230:233], v[124:127]
	ds_read_b128 v[218:221], v245 offset:8192
	ds_read_b128 v[222:225], v245 offset:10240
	ds_read_b128 v[226:229], v245 offset:12288
	ds_read_b128 v[230:233], v245 offset:14336
	s_waitcnt vmcnt(16)
	s_waitcnt lgkmcnt(4)
	v_mfma_f32_16x16x32_bf16 v[0:3], v[144:147], v[198:201], v[0:3]
	v_mfma_f32_16x16x32_bf16 v[32:35], v[148:151], v[198:201], v[32:35]
	v_mfma_f32_16x16x32_bf16 v[64:67], v[152:155], v[198:201], v[64:67]
	v_mfma_f32_16x16x32_bf16 v[96:99], v[156:159], v[198:201], v[96:99]
	global_load_dwordx4 v[128:131], v238, s[14:15]
	v_mfma_f32_16x16x32_bf16 v[4:7], v[144:147], v[202:205], v[4:7]
	v_mfma_f32_16x16x32_bf16 v[36:39], v[148:151], v[202:205], v[36:39]
	v_mfma_f32_16x16x32_bf16 v[68:71], v[152:155], v[202:205], v[68:71]
	v_mfma_f32_16x16x32_bf16 v[100:103], v[156:159], v[202:205], v[100:103]
	global_load_dwordx4 v[132:135], v239, s[14:15]
	v_mfma_f32_16x16x32_bf16 v[8:11], v[144:147], v[210:213], v[8:11]
	v_mfma_f32_16x16x32_bf16 v[40:43], v[148:151], v[210:213], v[40:43]
	v_mfma_f32_16x16x32_bf16 v[72:75], v[152:155], v[210:213], v[72:75]
	v_mfma_f32_16x16x32_bf16 v[104:107], v[156:159], v[210:213], v[104:107]
	global_load_dwordx4 v[136:139], v240, s[14:15]
	v_mfma_f32_16x16x32_bf16 v[12:15], v[144:147], v[214:217], v[12:15]
	v_mfma_f32_16x16x32_bf16 v[44:47], v[148:151], v[214:217], v[44:47]
	v_mfma_f32_16x16x32_bf16 v[76:79], v[152:155], v[214:217], v[76:79]
	v_mfma_f32_16x16x32_bf16 v[108:111], v[156:159], v[214:217], v[108:111]
	global_load_dwordx4 v[140:143], v241, s[14:15]
	s_cmp_eq_u32 s19, 31
	s_cbranch_scc1 .Lg3_sww2
	s_add_u32 s14, s14, 1024
	s_addc_u32 s15, s15, 0
	s_branch .Lg3_swdw2

.Lg3_wndw2:
.Lg3_swdw2:
	s_add_i32 s19, s19, 1
	s_waitcnt lgkmcnt(0)
	v_mfma_f32_16x16x32_bf16 v[16:19], v[144:147], v[218:221], v[16:19]
	v_mfma_f32_16x16x32_bf16 v[48:51], v[148:151], v[218:221], v[48:51]
	v_mfma_f32_16x16x32_bf16 v[80:83], v[152:155], v[218:221], v[80:83]
	v_mfma_f32_16x16x32_bf16 v[112:115], v[156:159], v[218:221], v[112:115]
	v_mfma_f32_16x16x32_bf16 v[20:23], v[144:147], v[222:225], v[20:23]
	v_mfma_f32_16x16x32_bf16 v[52:55], v[148:151], v[222:225], v[52:55]
	v_mfma_f32_16x16x32_bf16 v[84:87], v[152:155], v[222:225], v[84:87]
	v_mfma_f32_16x16x32_bf16 v[116:119], v[156:159], v[222:225], v[116:119]
	v_mfma_f32_16x16x32_bf16 v[24:27], v[144:147], v[226:229], v[24:27]
	v_mfma_f32_16x16x32_bf16 v[56:59], v[148:151], v[226:229], v[56:59]
	v_mfma_f32_16x16x32_bf16 v[88:91], v[152:155], v[226:229], v[88:91]
	v_mfma_f32_16x16x32_bf16 v[120:123], v[156:159], v[226:229], v[120:123]
	v_mfma_f32_16x16x32_bf16 v[28:31], v[144:147], v[230:233], v[28:31]
	v_mfma_f32_16x16x32_bf16 v[60:63], v[148:151], v[230:233], v[60:63]
	v_mfma_f32_16x16x32_bf16 v[92:95], v[152:155], v[230:233], v[92:95]
	v_mfma_f32_16x16x32_bf16 v[124:127], v[156:159], v[230:233], v[124:127]
	s_add_i32 s16, s16, 0x4000
	s_cmp_lt_u32 s16, 0xc000
	s_cselect_b32 s16, s16, 0
	s_add_i32 s17, s17, 0x4000
	s_cmp_lt_u32 s17, 0xc000
	s_cselect_b32 s17, s17, 0
	s_add_i32 s18, s18, 1
	s_waitcnt vmcnt(12)
	s_barrier
	global_load_dwordx4 v[144:147], v238, s[14:15]
	global_load_dwordx4 v[148:151], v239, s[14:15]
	global_load_dwordx4 v[152:155], v240, s[14:15]
	global_load_dwordx4 v[156:159], v241, s[14:15]
	s_cmp_eq_u32 s19, 31
	s_cbranch_scc1 .Lg3_sww3
	s_add_u32 s14, s14, 1024
	s_addc_u32 s15, s15, 0
	s_branch .Lg3_swdw3

.Lg3_nda4:
.Lg3_sada4:
	ds_read_b128 v[198:201], v245 offset:0
	ds_read_b128 v[202:205], v245 offset:2048
	ds_read_b128 v[210:213], v245 offset:4096
	ds_read_b128 v[214:217], v245 offset:6144
	s_waitcnt lgkmcnt(4)
	v_mfma_f32_16x16x32_bf16 v[16:19], v[160:163], v[218:221], v[16:19]
	v_mfma_f32_16x16x32_bf16 v[48:51], v[164:167], v[218:221], v[48:51]
	v_mfma_f32_16x16x32_bf16 v[80:83], v[168:171], v[218:221], v[80:83]
	v_mfma_f32_16x16x32_bf16 v[112:115], v[172:175], v[218:221], v[112:115]
	v_mfma_f32_16x16x32_bf16 v[20:23], v[160:163], v[222:225], v[20:23]
	v_mfma_f32_16x16x32_bf16 v[52:55], v[164:167], v[222:225], v[52:55]
	v_mfma_f32_16x16x32_bf16 v[84:87], v[168:171], v[222:225], v[84:87]
	v_mfma_f32_16x16x32_bf16 v[116:119], v[172:175], v[222:225], v[116:119]
	v_mfma_f32_16x16x32_bf16 v[24:27], v[160:163], v[226:229], v[24:27]
	v_mfma_f32_16x16x32_bf16 v[56:59], v[164:167], v[226:229], v[56:59]
	v_mfma_f32_16x16x32_bf16 v[88:91], v[168:171], v[226:229], v[88:91]
	v_mfma_f32_16x16x32_bf16 v[120:123], v[172:175], v[226:229], v[120:123]
	v_mfma_f32_16x16x32_bf16 v[28:31], v[160:163], v[230:233], v[28:31]
	v_mfma_f32_16x16x32_bf16 v[60:63], v[164:167], v[230:233], v[60:63]
	v_mfma_f32_16x16x32_bf16 v[92:95], v[168:171], v[230:233], v[92:95]
	v_mfma_f32_16x16x32_bf16 v[124:127], v[172:175], v[230:233], v[124:127]
	ds_read_b128 v[218:221], v245 offset:8192
	ds_read_b128 v[222:225], v245 offset:10240
	ds_read_b128 v[226:229], v245 offset:12288
	ds_read_b128 v[230:233], v245 offset:14336
	s_waitcnt vmcnt(16)
	s_waitcnt lgkmcnt(4)
	v_mfma_f32_16x16x32_bf16 v[0:3], v[176:179], v[198:201], v[0:3]
	v_mfma_f32_16x16x32_bf16 v[32:35], v[182:185], v[198:201], v[32:35]
	v_mfma_f32_16x16x32_bf16 v[64:67], v[186:189], v[198:201], v[64:67]
	v_mfma_f32_16x16x32_bf16 v[96:99], v[194:197], v[198:201], v[96:99]
	global_load_dwordx4 v[160:163], v238, s[14:15]
	v_mfma_f32_16x16x32_bf16 v[4:7], v[176:179], v[202:205], v[4:7]
	v_mfma_f32_16x16x32_bf16 v[36:39], v[182:185], v[202:205], v[36:39]
	v_mfma_f32_16x16x32_bf16 v[68:71], v[186:189], v[202:205], v[68:71]
	v_mfma_f32_16x16x32_bf16 v[100:103], v[194:197], v[202:205], v[100:103]
	global_load_dwordx4 v[164:167], v239, s[14:15]
	v_mfma_f32_16x16x32_bf16 v[8:11], v[176:179], v[210:213], v[8:11]
	v_mfma_f32_16x16x32_bf16 v[40:43], v[182:185], v[210:213], v[40:43]
	v_mfma_f32_16x16x32_bf16 v[72:75], v[186:189], v[210:213], v[72:75]
	v_mfma_f32_16x16x32_bf16 v[104:107], v[194:197], v[210:213], v[104:107]
	global_load_dwordx4 v[168:171], v240, s[14:15]
	v_mfma_f32_16x16x32_bf16 v[12:15], v[176:179], v[214:217], v[12:15]
	v_mfma_f32_16x16x32_bf16 v[44:47], v[182:185], v[214:217], v[44:47]
	v_mfma_f32_16x16x32_bf16 v[76:79], v[186:189], v[214:217], v[76:79]
	v_mfma_f32_16x16x32_bf16 v[108:111], v[194:197], v[214:217], v[108:111]
	global_load_dwordx4 v[172:175], v241, s[14:15]
	s_cmp_eq_u32 s19, 31
	s_cbranch_scc1 .Lg3_sww5
	s_add_u32 s14, s14, 1024
	s_addc_u32 s15, s15, 0
	s_branch .Lg3_swdw5

.Lg3_wndw5:
.Lg3_swdw5:
	s_add_i32 s19, s19, 1
	s_waitcnt lgkmcnt(0)
	v_mfma_f32_16x16x32_bf16 v[16:19], v[176:179], v[218:221], v[16:19]
	v_mfma_f32_16x16x32_bf16 v[48:51], v[182:185], v[218:221], v[48:51]
	v_mfma_f32_16x16x32_bf16 v[80:83], v[186:189], v[218:221], v[80:83]
	v_mfma_f32_16x16x32_bf16 v[112:115], v[194:197], v[218:221], v[112:115]
	v_mfma_f32_16x16x32_bf16 v[20:23], v[176:179], v[222:225], v[20:23]
	v_mfma_f32_16x16x32_bf16 v[52:55], v[182:185], v[222:225], v[52:55]
	v_mfma_f32_16x16x32_bf16 v[84:87], v[186:189], v[222:225], v[84:87]
	v_mfma_f32_16x16x32_bf16 v[116:119], v[194:197], v[222:225], v[116:119]
	v_mfma_f32_16x16x32_bf16 v[24:27], v[176:179], v[226:229], v[24:27]
	v_mfma_f32_16x16x32_bf16 v[56:59], v[182:185], v[226:229], v[56:59]
	v_mfma_f32_16x16x32_bf16 v[88:91], v[186:189], v[226:229], v[88:91]
	v_mfma_f32_16x16x32_bf16 v[120:123], v[194:197], v[226:229], v[120:123]
	v_mfma_f32_16x16x32_bf16 v[28:31], v[176:179], v[230:233], v[28:31]
	v_mfma_f32_16x16x32_bf16 v[60:63], v[182:185], v[230:233], v[60:63]
	v_mfma_f32_16x16x32_bf16 v[92:95], v[186:189], v[230:233], v[92:95]
	v_mfma_f32_16x16x32_bf16 v[124:127], v[194:197], v[230:233], v[124:127]
	s_add_i32 s16, s16, 0x4000
	s_cmp_lt_u32 s16, 0xc000
	s_cselect_b32 s16, s16, 0
	s_add_i32 s17, s17, 0x4000
	s_cmp_lt_u32 s17, 0xc000
	s_cselect_b32 s17, s17, 0
	s_add_i32 s18, s18, 1
	s_cmp_lt_u32 s18, 16
	s_cbranch_scc1 .Lg3_loop
	s_nop 7
	s_nop 7
	v_and_b32_e32 v198, 63, v208
	v_lshrrev_b32_e32 v199, 6, v208
	v_and_b32_e32 v200, 15, v198
	v_lshrrev_b32_e32 v201, 4, v198
	s_add_i32 s21, s11, s10
	s_and_b32 s21, s21, 3
	s_lshl_b32 s21, s21, 9
	s_lshl_b32 s2, s10, 18
	s_add_i32 s2, s2, s21
	s_add_i32 s2, s2, 0x26000000
	v_lshlrev_b32_e32 v244, 11, v200
	v_lshl_add_u32 v244, v199, 7, v244
	v_lshl_add_u32 v244, v201, 3, v244
	v_add_u32_e32 v244, s2, v244
	v_mov_b32_e32 v245, s93
	v_add_co_u32_e32 v244, vcc, s92, v244
	s_nop 1
	v_addc_co_u32_e32 v245, vcc, 0, v245, vcc
	v_mul_f32_e32 v0, v246, v0
	v_mul_f32_e32 v1, v246, v1
	v_mul_f32_e32 v2, v246, v2
	v_mul_f32_e32 v3, v246, v3
	v_cvt_pk_bf16_f32 v202, v0, v1
	v_cvt_pk_bf16_f32 v203, v2, v3
	global_store_dwordx2 v[244:245], v[202:203], off offset:0
	v_mul_f32_e32 v32, v246, v32
	v_mul_f32_e32 v33, v246, v33
	v_mul_f32_e32 v34, v246, v34
	v_mul_f32_e32 v35, v246, v35
	v_cvt_pk_bf16_f32 v204, v32, v33
	v_cvt_pk_bf16_f32 v205, v34, v35
	global_store_dwordx2 v[244:245], v[204:205], off offset:32
	v_mul_f32_e32 v64, v246, v64
	v_mul_f32_e32 v65, v246, v65
	v_mul_f32_e32 v66, v246, v66
	v_mul_f32_e32 v67, v246, v67
	v_cvt_pk_bf16_f32 v210, v64, v65
	v_cvt_pk_bf16_f32 v211, v66, v67
	global_store_dwordx2 v[244:245], v[210:211], off offset:64
	v_mul_f32_e32 v96, v246, v96
	v_mul_f32_e32 v97, v246, v97
	v_mul_f32_e32 v98, v246, v98
	v_mul_f32_e32 v99, v246, v99
	v_cvt_pk_bf16_f32 v212, v96, v97
	v_cvt_pk_bf16_f32 v213, v98, v99
	global_store_dwordx2 v[244:245], v[212:213], off offset:96
	v_add_co_u32_e32 v244, vcc, 0x8000, v244
	s_nop 1
	v_addc_co_u32_e32 v245, vcc, 0, v245, vcc
	v_mul_f32_e32 v4, v247, v4
	v_mul_f32_e32 v5, v247, v5
	v_mul_f32_e32 v6, v247, v6
	v_mul_f32_e32 v7, v247, v7
	v_cvt_pk_bf16_f32 v202, v4, v5
	v_cvt_pk_bf16_f32 v203, v6, v7
	global_store_dwordx2 v[244:245], v[202:203], off offset:0
	v_mul_f32_e32 v36, v247, v36
	v_mul_f32_e32 v37, v247, v37
	v_mul_f32_e32 v38, v247, v38
	v_mul_f32_e32 v39, v247, v39
	v_cvt_pk_bf16_f32 v204, v36, v37
	v_cvt_pk_bf16_f32 v205, v38, v39
	global_store_dwordx2 v[244:245], v[204:205], off offset:32
	v_mul_f32_e32 v68, v247, v68
	v_mul_f32_e32 v69, v247, v69
	v_mul_f32_e32 v70, v247, v70
	v_mul_f32_e32 v71, v247, v71
	v_cvt_pk_bf16_f32 v210, v68, v69
	v_cvt_pk_bf16_f32 v211, v70, v71
	global_store_dwordx2 v[244:245], v[210:211], off offset:64
	v_mul_f32_e32 v100, v247, v100
	v_mul_f32_e32 v101, v247, v101
	v_mul_f32_e32 v102, v247, v102
	v_mul_f32_e32 v103, v247, v103
	v_cvt_pk_bf16_f32 v212, v100, v101
	v_cvt_pk_bf16_f32 v213, v102, v103
	global_store_dwordx2 v[244:245], v[212:213], off offset:96
	v_add_co_u32_e32 v244, vcc, 0x8000, v244
	s_nop 1
	v_addc_co_u32_e32 v245, vcc, 0, v245, vcc
	v_mul_f32_e32 v8, v248, v8
	v_mul_f32_e32 v9, v248, v9
	v_mul_f32_e32 v10, v248, v10
	v_mul_f32_e32 v11, v248, v11
	v_cvt_pk_bf16_f32 v202, v8, v9
	v_cvt_pk_bf16_f32 v203, v10, v11
	global_store_dwordx2 v[244:245], v[202:203], off offset:0
	v_mul_f32_e32 v40, v248, v40
	v_mul_f32_e32 v41, v248, v41
	v_mul_f32_e32 v42, v248, v42
	v_mul_f32_e32 v43, v248, v43
	v_cvt_pk_bf16_f32 v204, v40, v41
	v_cvt_pk_bf16_f32 v205, v42, v43
	global_store_dwordx2 v[244:245], v[204:205], off offset:32
	v_mul_f32_e32 v72, v248, v72
	v_mul_f32_e32 v73, v248, v73
	v_mul_f32_e32 v74, v248, v74
	v_mul_f32_e32 v75, v248, v75
	v_cvt_pk_bf16_f32 v210, v72, v73
	v_cvt_pk_bf16_f32 v211, v74, v75
	global_store_dwordx2 v[244:245], v[210:211], off offset:64
	v_mul_f32_e32 v104, v248, v104
	v_mul_f32_e32 v105, v248, v105
	v_mul_f32_e32 v106, v248, v106
	v_mul_f32_e32 v107, v248, v107
	v_cvt_pk_bf16_f32 v212, v104, v105
	v_cvt_pk_bf16_f32 v213, v106, v107
	global_store_dwordx2 v[244:245], v[212:213], off offset:96
	v_add_co_u32_e32 v244, vcc, 0x8000, v244
	s_nop 1
	v_addc_co_u32_e32 v245, vcc, 0, v245, vcc
	v_mul_f32_e32 v12, v249, v12
	v_mul_f32_e32 v13, v249, v13
	v_mul_f32_e32 v14, v249, v14
	v_mul_f32_e32 v15, v249, v15
	v_cvt_pk_bf16_f32 v202, v12, v13
	v_cvt_pk_bf16_f32 v203, v14, v15
	global_store_dwordx2 v[244:245], v[202:203], off offset:0
	v_mul_f32_e32 v44, v249, v44
	v_mul_f32_e32 v45, v249, v45
	v_mul_f32_e32 v46, v249, v46
	v_mul_f32_e32 v47, v249, v47
	v_cvt_pk_bf16_f32 v204, v44, v45
	v_cvt_pk_bf16_f32 v205, v46, v47
	global_store_dwordx2 v[244:245], v[204:205], off offset:32
	v_mul_f32_e32 v76, v249, v76
	v_mul_f32_e32 v77, v249, v77
	v_mul_f32_e32 v78, v249, v78
	v_mul_f32_e32 v79, v249, v79
	v_cvt_pk_bf16_f32 v210, v76, v77
	v_cvt_pk_bf16_f32 v211, v78, v79
	global_store_dwordx2 v[244:245], v[210:211], off offset:64
	v_mul_f32_e32 v108, v249, v108
	v_mul_f32_e32 v109, v249, v109
	v_mul_f32_e32 v110, v249, v110
	v_mul_f32_e32 v111, v249, v111
	v_cvt_pk_bf16_f32 v212, v108, v109
	v_cvt_pk_bf16_f32 v213, v110, v111
	global_store_dwordx2 v[244:245], v[212:213], off offset:96
	v_add_co_u32_e32 v244, vcc, 0x8000, v244
	s_nop 1
	v_addc_co_u32_e32 v245, vcc, 0, v245, vcc
	v_mul_f32_e32 v16, v250, v16
	v_mul_f32_e32 v17, v250, v17
	v_mul_f32_e32 v18, v250, v18
	v_mul_f32_e32 v19, v250, v19
	v_cvt_pk_bf16_f32 v202, v16, v17
	v_cvt_pk_bf16_f32 v203, v18, v19
	global_store_dwordx2 v[244:245], v[202:203], off offset:0
	v_mul_f32_e32 v48, v250, v48
	v_mul_f32_e32 v49, v250, v49
	v_mul_f32_e32 v50, v250, v50
	v_mul_f32_e32 v51, v250, v51
	v_cvt_pk_bf16_f32 v204, v48, v49
	v_cvt_pk_bf16_f32 v205, v50, v51
	global_store_dwordx2 v[244:245], v[204:205], off offset:32
	v_mul_f32_e32 v80, v250, v80
	v_mul_f32_e32 v81, v250, v81
	v_mul_f32_e32 v82, v250, v82
	v_mul_f32_e32 v83, v250, v83
	v_cvt_pk_bf16_f32 v210, v80, v81
	v_cvt_pk_bf16_f32 v211, v82, v83
	global_store_dwordx2 v[244:245], v[210:211], off offset:64
	v_mul_f32_e32 v112, v250, v112
	v_mul_f32_e32 v113, v250, v113
	v_mul_f32_e32 v114, v250, v114
	v_mul_f32_e32 v115, v250, v115
	v_cvt_pk_bf16_f32 v212, v112, v113
	v_cvt_pk_bf16_f32 v213, v114, v115
	global_store_dwordx2 v[244:245], v[212:213], off offset:96
	v_add_co_u32_e32 v244, vcc, 0x8000, v244
	s_nop 1
	v_addc_co_u32_e32 v245, vcc, 0, v245, vcc
	v_mul_f32_e32 v20, v251, v20
	v_mul_f32_e32 v21, v251, v21
	v_mul_f32_e32 v22, v251, v22
	v_mul_f32_e32 v23, v251, v23
	v_cvt_pk_bf16_f32 v202, v20, v21
	v_cvt_pk_bf16_f32 v203, v22, v23
	global_store_dwordx2 v[244:245], v[202:203], off offset:0
	v_mul_f32_e32 v52, v251, v52
	v_mul_f32_e32 v53, v251, v53
	v_mul_f32_e32 v54, v251, v54
	v_mul_f32_e32 v55, v251, v55
	v_cvt_pk_bf16_f32 v204, v52, v53
	v_cvt_pk_bf16_f32 v205, v54, v55
	global_store_dwordx2 v[244:245], v[204:205], off offset:32
	v_mul_f32_e32 v84, v251, v84
	v_mul_f32_e32 v85, v251, v85
	v_mul_f32_e32 v86, v251, v86
	v_mul_f32_e32 v87, v251, v87
	v_cvt_pk_bf16_f32 v210, v84, v85
	v_cvt_pk_bf16_f32 v211, v86, v87
	global_store_dwordx2 v[244:245], v[210:211], off offset:64
	v_mul_f32_e32 v116, v251, v116
	v_mul_f32_e32 v117, v251, v117
	v_mul_f32_e32 v118, v251, v118
	v_mul_f32_e32 v119, v251, v119
	v_cvt_pk_bf16_f32 v212, v116, v117
	v_cvt_pk_bf16_f32 v213, v118, v119
	global_store_dwordx2 v[244:245], v[212:213], off offset:96
	v_add_co_u32_e32 v244, vcc, 0x8000, v244
	s_nop 1
	v_addc_co_u32_e32 v245, vcc, 0, v245, vcc
	v_mul_f32_e32 v24, v252, v24
	v_mul_f32_e32 v25, v252, v25
	v_mul_f32_e32 v26, v252, v26
	v_mul_f32_e32 v27, v252, v27
	v_cvt_pk_bf16_f32 v202, v24, v25
	v_cvt_pk_bf16_f32 v203, v26, v27
	global_store_dwordx2 v[244:245], v[202:203], off offset:0
	v_mul_f32_e32 v56, v252, v56
	v_mul_f32_e32 v57, v252, v57
	v_mul_f32_e32 v58, v252, v58
	v_mul_f32_e32 v59, v252, v59
	v_cvt_pk_bf16_f32 v204, v56, v57
	v_cvt_pk_bf16_f32 v205, v58, v59
	global_store_dwordx2 v[244:245], v[204:205], off offset:32
	v_mul_f32_e32 v88, v252, v88
	v_mul_f32_e32 v89, v252, v89
	v_mul_f32_e32 v90, v252, v90
	v_mul_f32_e32 v91, v252, v91
	v_cvt_pk_bf16_f32 v210, v88, v89
	v_cvt_pk_bf16_f32 v211, v90, v91
	global_store_dwordx2 v[244:245], v[210:211], off offset:64
	v_mul_f32_e32 v120, v252, v120
	v_mul_f32_e32 v121, v252, v121
	v_mul_f32_e32 v122, v252, v122
	v_mul_f32_e32 v123, v252, v123
	v_cvt_pk_bf16_f32 v212, v120, v121
	v_cvt_pk_bf16_f32 v213, v122, v123
	global_store_dwordx2 v[244:245], v[212:213], off offset:96
	v_add_co_u32_e32 v244, vcc, 0x8000, v244
	s_nop 1
	v_addc_co_u32_e32 v245, vcc, 0, v245, vcc
	v_mul_f32_e32 v28, v253, v28
	v_mul_f32_e32 v29, v253, v29
	v_mul_f32_e32 v30, v253, v30
	v_mul_f32_e32 v31, v253, v31
	v_cvt_pk_bf16_f32 v202, v28, v29
	v_cvt_pk_bf16_f32 v203, v30, v31
	global_store_dwordx2 v[244:245], v[202:203], off offset:0
	v_mul_f32_e32 v60, v253, v60
	v_mul_f32_e32 v61, v253, v61
	v_mul_f32_e32 v62, v253, v62
	v_mul_f32_e32 v63, v253, v63
	v_cvt_pk_bf16_f32 v204, v60, v61
	v_cvt_pk_bf16_f32 v205, v62, v63
	global_store_dwordx2 v[244:245], v[204:205], off offset:32
	v_mul_f32_e32 v92, v253, v92
	v_mul_f32_e32 v93, v253, v93
	v_mul_f32_e32 v94, v253, v94
	v_mul_f32_e32 v95, v253, v95
	v_cvt_pk_bf16_f32 v210, v92, v93
	v_cvt_pk_bf16_f32 v211, v94, v95
	global_store_dwordx2 v[244:245], v[210:211], off offset:64
	v_mul_f32_e32 v124, v253, v124
	v_mul_f32_e32 v125, v253, v125
	v_mul_f32_e32 v126, v253, v126
	v_mul_f32_e32 v127, v253, v127
	v_cvt_pk_bf16_f32 v212, v124, v125
	v_cvt_pk_bf16_f32 v213, v126, v127
	global_store_dwordx2 v[244:245], v[212:213], off offset:96
	s_add_i32 s11, s11, 1
	s_cmp_lt_u32 s11, 4
	s_cbranch_scc1 .Lg3_chunk
	s_mov_b32 s11, 0
	s_add_i32 s10, s10, s95
	s_cmpk_gt_i32 s10, 0x1ff
	s_cbranch_scc1 .Lg3_done
	v_and_b32_e32 v244, 15, v208
	v_lshlrev_b32_e32 v244, 2, v244
	s_lshl_b32 s2, s10, 9
	s_add_i32 s2, s2, 0x36c80000
	v_add_u32_e32 v244, s2, v244
	v_mov_b32_e32 v245, s93
	v_add_co_u32_e32 v244, vcc, s92, v244
	s_nop 1
	v_addc_co_u32_e32 v245, vcc, 0, v245, vcc
	global_load_dword v246, v[244:245], off
	global_load_dword v247, v[244:245], off offset:64
	global_load_dword v248, v[244:245], off offset:128
	global_load_dword v249, v[244:245], off offset:192
	global_load_dword v250, v[244:245], off offset:256
	global_load_dword v251, v[244:245], off offset:320
	global_load_dword v252, v[244:245], off offset:384
	global_load_dword v253, v[244:245], off offset:448
	s_branch .Lg3_chunk
